# plus: static s_setprio 1 of waves 0-3 in the GQA units removed (with the shortened instruction streams it no longer pays)
# baseline (speedup 1.0000x reference)
; #define PHON(k) constexpr (((MK_PHMASK) >> (k)) & 1)
; __global__ void __launch_bounds__(512, 2) mega_fwd(Args args) {
;     ...
;             if (wave0 < 4) __builtin_amdgcn_s_setprio(1);
;             if PHON(8) for (int u = bid; u < 256; u += G) { const int xq = u & 7, hd = xq & 3, qb = (u >> 3) + 32 * (xq >> 2), q0 = qb * 256;
;                 { const float sc = 0.08838834764831845f;
;                   if (wave0 < 4) att::attn_unit<8, 0, 0, 1, 0, 0, 0>(QC + (size_t)q0 * 512 + hd * 128, 512, KC + (hd >> 1) * 128, 256, nullptr, 0, PROJ + C_CV + (hd >> 1) * 128, LDP,
;                                            0, S, q0, nullptr, 0.f, 0.f, MIX + (size_t)q0 * DM + 1024 + hd * 128, DM, nullptr, 0.f, nullptr, 0.f, (char*)lds, wave0); else att::attn_unit<8, 0, 0, 1, 0, 0, 1>(QC + (size_t)q0 * 512 + hd * 128, 512, KC + (hd >> 1) * 128, 256, nullptr, 0, PROJ + C_CV + (hd >> 1) * 128, LDP,
;                                            0, S, q0, nullptr, 0.f, 0.f, MIX + (size_t)q0 * DM + 1024 + hd * 128, DM, nullptr, 0.f, nullptr, 0.f, (char*)lds, wave0); }
;             }
;             __builtin_amdgcn_s_setprio(0);
.LBB0_411:
	v_readlane_b32 s4, v254, 17
	v_readlane_b32 s5, v254, 18
	s_and_b64 vcc, exec, s[4:5]
	s_cbranch_vccz .LBB0_413
.LBB0_413:
	v_readlane_b32 s6, v254, 15
	v_readlane_b32 s7, v254, 16
	s_mov_b64 s[4:5], -1
	s_and_b64 vcc, exec, s[6:7]
	s_cbranch_vccz .LBB0_415
	s_setprio 0
	s_mov_b64 s[4:5], 0
